# seam 0: non-leader workgroups poll the cross-XCD release word directly (one hop fewer)
# speedup vs baseline: 1.0051x; 1.0029x over previous
.LBB0_61:
	s_or_b64 exec, exec, s[10:11]
	v_cvt_f32_u32_e32 v4, v2
	s_waitcnt vmcnt(0)
	v_readfirstlane_b32 s3, v3
	v_sub_u32_e32 v3, 0, v2
	v_rcp_iflag_f32_e32 v4, v4
	v_add_u32_e32 v5, s3, v1
	v_mul_f32_e32 v4, 0x4f7ffffe, v4
	v_cvt_u32_f32_e32 v4, v4
	v_mul_lo_u32 v1, v3, v4
	v_mul_hi_u32 v1, v4, v1
	v_add_u32_e32 v1, v4, v1
	v_mul_hi_u32 v1, v5, v1
	v_mul_lo_u32 v3, v1, v2
	v_sub_u32_e32 v3, v5, v3
	v_add_u32_e32 v4, 1, v1
	v_cmp_ge_u32_e32 vcc, v3, v2
	s_nop 1
	v_cndmask_b32_e32 v1, v1, v4, vcc
	v_sub_u32_e32 v4, v3, v2
	v_cndmask_b32_e32 v3, v3, v4, vcc
	v_add_u32_e32 v4, 1, v1
	v_cmp_ge_u32_e32 vcc, v3, v2
	v_add_u32_e32 v3, 1, v5
	s_nop 0
	v_cndmask_b32_e32 v1, v1, v4, vcc
	v_mul_lo_u32 v4, v2, v1
	v_add_u32_e32 v2, v4, v2
	v_cmp_ne_u32_e32 vcc, v3, v2
	s_and_saveexec_b64 s[8:9], vcc
	s_xor_b64 s[8:9], exec, s[8:9]
	s_cbranch_execz .LBB0_75
	s_waitcnt lgkmcnt(0)
	v_mov_b32_e32 v0, 0x3100
	global_load_dword v0, v0, s[92:93] offset:1024 sc1
	s_add_u32 s44, s92, 0x3500
	s_addc_u32 s45, s93, 0
	s_waitcnt vmcnt(0)
	v_cmp_eq_u32_e32 vcc, v0, v1
	s_and_saveexec_b64 s[38:39], vcc
	s_cbranch_execz .LBB0_74
	s_add_u32 s40, s30, 0xfc00200
	s_addc_u32 s41, s31, 0
	s_mov_b32 s3, 1
	s_mov_b64 s[60:61], 0
	v_mov_b32_e32 v0, 0
	s_branch .LBB0_65
